# GEMM K-loops: s_setprio roles inverted (load segments at priority 1, MFMA segments at 0)
# baseline (speedup 1.0000x reference)
.LBB0_120:
	ds_read_b128 v[130:133], v245
	ds_read_b128 v[134:137], v245 offset:1024
	ds_read_b128 v[138:141], v245 offset:2048
	ds_read_b128 v[142:145], v245 offset:3072
	s_waitcnt vmcnt(0)
	ds_read_b128 v[146:149], v246
	ds_read_b128 v[150:153], v246 offset:1024
	ds_read_b128 v[154:157], v246 offset:2048
	ds_read_b128 v[158:161], v246 offset:3072
	s_add_u32 s16, s6, 0xfffc0080
	s_addc_u32 s17, s7, -1
	s_cmp_eq_u32 s40, 12
	s_cselect_b32 s79, s1, s17
	s_cselect_b32 s78, s2, s16
	s_cselect_b32 s17, s3, s37
	s_cselect_b32 s16, s9, s35
	s_add_i32 m0, s71, 0xc000
	ds_read_b128 v[162:165], v247
	ds_read_b128 v[166:169], v247 offset:1024
	ds_read_b128 v[170:173], v247 offset:2048
	ds_read_b128 v[174:177], v247 offset:3072
	ds_read_b128 v[178:181], v247 offset:4096
	ds_read_b128 v[182:185], v247 offset:5120
	ds_read_b128 v[186:189], v247 offset:6144
	ds_read_b128 v[190:193], v247 offset:7168
	global_load_lds_dwordx4 v226, s[6:7]
	s_add_i32 m0, s71, 0xe000
	s_nop 0
	global_load_lds_dwordx4 v228, s[6:7]
	s_waitcnt vmcnt(8)
	s_waitcnt lgkmcnt(0)
	s_barrier
	s_setprio 0
	s_waitcnt lgkmcnt(0)
	v_mfma_f32_16x16x32_bf16 v[126:129], v[130:133], v[162:165], v[126:129]
	v_mfma_f32_16x16x32_bf16 v[122:125], v[138:141], v[162:165], v[122:125]
	v_mfma_f32_16x16x32_bf16 v[110:113], v[130:133], v[170:173], v[110:113]
	v_mfma_f32_16x16x32_bf16 v[106:109], v[138:141], v[170:173], v[106:109]
	v_mfma_f32_16x16x32_bf16 v[94:97], v[130:133], v[178:181], v[94:97]
	v_mfma_f32_16x16x32_bf16 v[90:93], v[138:141], v[178:181], v[90:93]
	v_mfma_f32_16x16x32_bf16 v[78:81], v[130:133], v[186:189], v[78:81]
	v_mfma_f32_16x16x32_bf16 v[74:77], v[138:141], v[186:189], v[74:77]
	v_mfma_f32_16x16x32_bf16 v[126:129], v[134:137], v[166:169], v[126:129]
	v_mfma_f32_16x16x32_bf16 v[122:125], v[142:145], v[166:169], v[122:125]
	v_mfma_f32_16x16x32_bf16 v[110:113], v[134:137], v[174:177], v[110:113]
	v_mfma_f32_16x16x32_bf16 v[106:109], v[142:145], v[174:177], v[106:109]
	v_mfma_f32_16x16x32_bf16 v[94:97], v[134:137], v[182:185], v[94:97]
	v_mfma_f32_16x16x32_bf16 v[90:93], v[142:145], v[182:185], v[90:93]
	v_mfma_f32_16x16x32_bf16 v[78:81], v[134:137], v[190:193], v[78:81]
	v_mfma_f32_16x16x32_bf16 v[74:77], v[142:145], v[190:193], v[74:77]
	s_setprio 1
	s_setprio 0
	v_mfma_f32_16x16x32_bf16 v[118:121], v[146:149], v[162:165], v[118:121]
	v_mfma_f32_16x16x32_bf16 v[114:117], v[154:157], v[162:165], v[114:117]
	v_mfma_f32_16x16x32_bf16 v[102:105], v[146:149], v[170:173], v[102:105]
	v_mfma_f32_16x16x32_bf16 v[98:101], v[154:157], v[170:173], v[98:101]
	v_mfma_f32_16x16x32_bf16 v[86:89], v[146:149], v[178:181], v[86:89]
	v_mfma_f32_16x16x32_bf16 v[82:85], v[154:157], v[178:181], v[82:85]
	v_mfma_f32_16x16x32_bf16 v[70:73], v[146:149], v[186:189], v[70:73]
	v_mfma_f32_16x16x32_bf16 v[66:69], v[154:157], v[186:189], v[66:69]
	v_mfma_f32_16x16x32_bf16 v[118:121], v[150:153], v[166:169], v[118:121]
	v_mfma_f32_16x16x32_bf16 v[114:117], v[158:161], v[166:169], v[114:117]
	v_mfma_f32_16x16x32_bf16 v[102:105], v[150:153], v[174:177], v[102:105]
	v_mfma_f32_16x16x32_bf16 v[98:101], v[158:161], v[174:177], v[98:101]
	v_mfma_f32_16x16x32_bf16 v[86:89], v[150:153], v[182:185], v[86:89]
	v_mfma_f32_16x16x32_bf16 v[82:85], v[158:161], v[182:185], v[82:85]
	v_mfma_f32_16x16x32_bf16 v[70:73], v[150:153], v[190:193], v[70:73]
	v_mfma_f32_16x16x32_bf16 v[66:69], v[158:161], v[190:193], v[66:69]
	s_setprio 1
	s_barrier
	s_add_i32 s41, s12, s39
	s_mov_b32 m0, s41
	ds_read_b128 v[162:165], v247 offset:16384
	ds_read_b128 v[166:169], v247 offset:17408
	ds_read_b128 v[170:173], v247 offset:18432
	ds_read_b128 v[174:177], v247 offset:19456
	ds_read_b128 v[178:181], v247 offset:20480
	ds_read_b128 v[182:185], v247 offset:21504
	ds_read_b128 v[186:189], v247 offset:22528
	ds_read_b128 v[190:193], v247 offset:23552
	global_load_lds_dwordx4 v212, s[16:17]
	s_add_i32 m0, s41, 0x2000
	s_add_u32 s42, s16, 0x40000
	s_addc_u32 s43, s17, 0
	s_add_i32 s41, s13, s39
	global_load_lds_dwordx4 v216, s[16:17]
	s_mov_b32 m0, s41
	s_nop 0
	global_load_lds_dwordx4 v212, s[42:43]
	s_add_i32 m0, s41, 0x2000
	s_nop 0
	global_load_lds_dwordx4 v216, s[42:43]
	s_mov_b32 m0, s71
	s_nop 0
	global_load_lds_dwordx4 v210, s[78:79]
	s_mov_b32 m0, s20
	s_nop 0
	global_load_lds_dwordx4 v214, s[78:79]
	s_waitcnt vmcnt(8)
	s_waitcnt lgkmcnt(0)
	s_barrier
	s_setprio 0
	s_waitcnt lgkmcnt(0)
	v_mfma_f32_16x16x32_bf16 v[62:65], v[130:133], v[162:165], v[62:65]
	v_mfma_f32_16x16x32_bf16 v[58:61], v[138:141], v[162:165], v[58:61]
	v_mfma_f32_16x16x32_bf16 v[46:49], v[130:133], v[170:173], v[46:49]
	v_mfma_f32_16x16x32_bf16 v[42:45], v[138:141], v[170:173], v[42:45]
	v_mfma_f32_16x16x32_bf16 v[30:33], v[130:133], v[178:181], v[30:33]
	v_mfma_f32_16x16x32_bf16 v[26:29], v[138:141], v[178:181], v[26:29]
	v_mfma_f32_16x16x32_bf16 v[14:17], v[130:133], v[186:189], v[14:17]
	v_mfma_f32_16x16x32_bf16 v[10:13], v[138:141], v[186:189], v[10:13]
	v_mfma_f32_16x16x32_bf16 v[62:65], v[134:137], v[166:169], v[62:65]
	v_mfma_f32_16x16x32_bf16 v[58:61], v[142:145], v[166:169], v[58:61]
	v_mfma_f32_16x16x32_bf16 v[46:49], v[134:137], v[174:177], v[46:49]
	v_mfma_f32_16x16x32_bf16 v[42:45], v[142:145], v[174:177], v[42:45]
	v_mfma_f32_16x16x32_bf16 v[30:33], v[134:137], v[182:185], v[30:33]
	v_mfma_f32_16x16x32_bf16 v[26:29], v[142:145], v[182:185], v[26:29]
	v_mfma_f32_16x16x32_bf16 v[14:17], v[134:137], v[190:193], v[14:17]
	v_mfma_f32_16x16x32_bf16 v[10:13], v[142:145], v[190:193], v[10:13]
	s_setprio 1
	s_setprio 0
	v_mfma_f32_16x16x32_bf16 v[54:57], v[146:149], v[162:165], v[54:57]
	v_mfma_f32_16x16x32_bf16 v[50:53], v[154:157], v[162:165], v[50:53]
	v_mfma_f32_16x16x32_bf16 v[38:41], v[146:149], v[170:173], v[38:41]
	v_mfma_f32_16x16x32_bf16 v[34:37], v[154:157], v[170:173], v[34:37]
	v_mfma_f32_16x16x32_bf16 v[22:25], v[146:149], v[178:181], v[22:25]
	v_mfma_f32_16x16x32_bf16 v[18:21], v[154:157], v[178:181], v[18:21]
	v_mfma_f32_16x16x32_bf16 v[6:9], v[146:149], v[186:189], v[6:9]
	v_mfma_f32_16x16x32_bf16 v[2:5], v[154:157], v[186:189], v[2:5]
	v_mfma_f32_16x16x32_bf16 v[54:57], v[150:153], v[166:169], v[54:57]
	v_mfma_f32_16x16x32_bf16 v[50:53], v[158:161], v[166:169], v[50:53]
	v_mfma_f32_16x16x32_bf16 v[38:41], v[150:153], v[174:177], v[38:41]
	v_mfma_f32_16x16x32_bf16 v[34:37], v[158:161], v[174:177], v[34:37]
	v_mfma_f32_16x16x32_bf16 v[22:25], v[150:153], v[182:185], v[22:25]
	v_mfma_f32_16x16x32_bf16 v[18:21], v[158:161], v[182:185], v[18:21]
	v_mfma_f32_16x16x32_bf16 v[6:9], v[150:153], v[190:193], v[6:9]
	v_mfma_f32_16x16x32_bf16 v[2:5], v[158:161], v[190:193], v[2:5]
	s_setprio 1
	s_barrier
	s_add_i32 s41, 0, 0x18000
	s_add_i32 s44, 0, 0x1c000
	v_add_u32_e32 v142, s41, v223
	v_add_u32_e32 v158, s44, v223
	ds_read_b128 v[130:133], v142
	ds_read_b128 v[134:137], v142 offset:1024
	ds_read_b128 v[138:141], v142 offset:2048
	ds_read_b128 v[142:145], v142 offset:3072
	ds_read_b128 v[146:149], v158
	ds_read_b128 v[150:153], v158 offset:1024
	ds_read_b128 v[154:157], v158 offset:2048
	ds_read_b128 v[158:161], v158 offset:3072
	s_add_u32 s42, s78, 0x40000
	s_addc_u32 s43, s79, 0
	s_mov_b32 m0, s21
	ds_read_b128 v[162:165], v247 offset:32768
	ds_read_b128 v[166:169], v247 offset:33792
	ds_read_b128 v[170:173], v247 offset:34816
	ds_read_b128 v[174:177], v247 offset:35840
	ds_read_b128 v[178:181], v247 offset:36864
	ds_read_b128 v[182:185], v247 offset:37888
	ds_read_b128 v[186:189], v247 offset:38912
	ds_read_b128 v[190:193], v247 offset:39936
	global_load_lds_dwordx4 v210, s[42:43]
	s_mov_b32 m0, s22
	s_nop 0
	global_load_lds_dwordx4 v214, s[42:43]
	s_waitcnt vmcnt(8)
	s_waitcnt lgkmcnt(0)
	s_barrier
	s_setprio 0
	s_waitcnt lgkmcnt(0)
	v_mfma_f32_16x16x32_bf16 v[126:129], v[130:133], v[162:165], v[126:129]
	v_mfma_f32_16x16x32_bf16 v[122:125], v[138:141], v[162:165], v[122:125]
	v_mfma_f32_16x16x32_bf16 v[110:113], v[130:133], v[170:173], v[110:113]
	v_mfma_f32_16x16x32_bf16 v[106:109], v[138:141], v[170:173], v[106:109]
	v_mfma_f32_16x16x32_bf16 v[94:97], v[130:133], v[178:181], v[94:97]
	v_mfma_f32_16x16x32_bf16 v[90:93], v[138:141], v[178:181], v[90:93]
	v_mfma_f32_16x16x32_bf16 v[78:81], v[130:133], v[186:189], v[78:81]
	v_mfma_f32_16x16x32_bf16 v[74:77], v[138:141], v[186:189], v[74:77]
	v_mfma_f32_16x16x32_bf16 v[126:129], v[134:137], v[166:169], v[126:129]
	v_mfma_f32_16x16x32_bf16 v[122:125], v[142:145], v[166:169], v[122:125]
	v_mfma_f32_16x16x32_bf16 v[110:113], v[134:137], v[174:177], v[110:113]
	v_mfma_f32_16x16x32_bf16 v[106:109], v[142:145], v[174:177], v[106:109]
	v_mfma_f32_16x16x32_bf16 v[94:97], v[134:137], v[182:185], v[94:97]
	v_mfma_f32_16x16x32_bf16 v[90:93], v[142:145], v[182:185], v[90:93]
	v_mfma_f32_16x16x32_bf16 v[78:81], v[134:137], v[190:193], v[78:81]
	v_mfma_f32_16x16x32_bf16 v[74:77], v[142:145], v[190:193], v[74:77]
	s_setprio 1
	s_setprio 0
	v_mfma_f32_16x16x32_bf16 v[118:121], v[146:149], v[162:165], v[118:121]
	v_mfma_f32_16x16x32_bf16 v[114:117], v[154:157], v[162:165], v[114:117]
	v_mfma_f32_16x16x32_bf16 v[102:105], v[146:149], v[170:173], v[102:105]
	v_mfma_f32_16x16x32_bf16 v[98:101], v[154:157], v[170:173], v[98:101]
	v_mfma_f32_16x16x32_bf16 v[86:89], v[146:149], v[178:181], v[86:89]
	v_mfma_f32_16x16x32_bf16 v[82:85], v[154:157], v[178:181], v[82:85]
	v_mfma_f32_16x16x32_bf16 v[70:73], v[146:149], v[186:189], v[70:73]
	v_mfma_f32_16x16x32_bf16 v[66:69], v[154:157], v[186:189], v[66:69]
	v_mfma_f32_16x16x32_bf16 v[118:121], v[150:153], v[166:169], v[118:121]
	v_mfma_f32_16x16x32_bf16 v[114:117], v[158:161], v[166:169], v[114:117]
	v_mfma_f32_16x16x32_bf16 v[102:105], v[150:153], v[174:177], v[102:105]
	v_mfma_f32_16x16x32_bf16 v[98:101], v[158:161], v[174:177], v[98:101]
	v_mfma_f32_16x16x32_bf16 v[86:89], v[150:153], v[182:185], v[86:89]
	v_mfma_f32_16x16x32_bf16 v[82:85], v[158:161], v[182:185], v[82:85]
	v_mfma_f32_16x16x32_bf16 v[70:73], v[150:153], v[190:193], v[70:73]
	v_mfma_f32_16x16x32_bf16 v[66:69], v[158:161], v[190:193], v[66:69]
	s_setprio 1
	s_barrier
	s_add_i32 s41, s41, s39
	s_add_i32 m0, s41, 0xffffff80
	ds_read_b128 v[162:165], v247 offset:49152
	ds_read_b128 v[166:169], v247 offset:50176
	ds_read_b128 v[170:173], v247 offset:51200
	ds_read_b128 v[174:177], v247 offset:52224
	ds_read_b128 v[178:181], v247 offset:53248
	ds_read_b128 v[182:185], v247 offset:54272
	ds_read_b128 v[186:189], v247 offset:55296
	ds_read_b128 v[190:193], v247 offset:56320
	global_load_lds_dwordx4 v212, s[16:17] offset:128
	s_add_i32 m0, s41, 0x1f80
	s_add_i32 s41, s44, s39
	global_load_lds_dwordx4 v216, s[16:17] offset:128
	s_add_u32 s16, s16, 0x40080
	s_addc_u32 s17, s17, 0
	s_mov_b32 m0, s41
	s_nop 0
	global_load_lds_dwordx4 v212, s[16:17]
	s_add_i32 m0, s41, 0x2000
	s_nop 0
	global_load_lds_dwordx4 v216, s[16:17]
	s_add_i32 m0, s14, 0xffffff80
	s_nop 0
	global_load_lds_dwordx4 v210, s[78:79] offset:128
	s_add_i32 m0, s15, 0xffffff80
	s_nop 0
	global_load_lds_dwordx4 v214, s[78:79] offset:128
	s_waitcnt vmcnt(8)
	s_waitcnt lgkmcnt(0)
	s_barrier
	s_setprio 0
	s_waitcnt lgkmcnt(0)
	v_mfma_f32_16x16x32_bf16 v[62:65], v[130:133], v[162:165], v[62:65]
	v_mfma_f32_16x16x32_bf16 v[58:61], v[138:141], v[162:165], v[58:61]
	v_mfma_f32_16x16x32_bf16 v[46:49], v[130:133], v[170:173], v[46:49]
	v_mfma_f32_16x16x32_bf16 v[42:45], v[138:141], v[170:173], v[42:45]
	v_mfma_f32_16x16x32_bf16 v[30:33], v[130:133], v[178:181], v[30:33]
	v_mfma_f32_16x16x32_bf16 v[26:29], v[138:141], v[178:181], v[26:29]
	v_mfma_f32_16x16x32_bf16 v[14:17], v[130:133], v[186:189], v[14:17]
	v_mfma_f32_16x16x32_bf16 v[10:13], v[138:141], v[186:189], v[10:13]
	v_mfma_f32_16x16x32_bf16 v[62:65], v[134:137], v[166:169], v[62:65]
	v_mfma_f32_16x16x32_bf16 v[58:61], v[142:145], v[166:169], v[58:61]
	v_mfma_f32_16x16x32_bf16 v[46:49], v[134:137], v[174:177], v[46:49]
	v_mfma_f32_16x16x32_bf16 v[42:45], v[142:145], v[174:177], v[42:45]
	v_mfma_f32_16x16x32_bf16 v[30:33], v[134:137], v[182:185], v[30:33]
	v_mfma_f32_16x16x32_bf16 v[26:29], v[142:145], v[182:185], v[26:29]
	v_mfma_f32_16x16x32_bf16 v[14:17], v[134:137], v[190:193], v[14:17]
	v_mfma_f32_16x16x32_bf16 v[10:13], v[142:145], v[190:193], v[10:13]
	s_setprio 1
	s_setprio 0
	v_mfma_f32_16x16x32_bf16 v[54:57], v[146:149], v[162:165], v[54:57]
	v_mfma_f32_16x16x32_bf16 v[50:53], v[154:157], v[162:165], v[50:53]
	v_mfma_f32_16x16x32_bf16 v[38:41], v[146:149], v[170:173], v[38:41]
	v_mfma_f32_16x16x32_bf16 v[34:37], v[154:157], v[170:173], v[34:37]
	v_mfma_f32_16x16x32_bf16 v[22:25], v[146:149], v[178:181], v[22:25]
	v_mfma_f32_16x16x32_bf16 v[18:21], v[154:157], v[178:181], v[18:21]
	v_mfma_f32_16x16x32_bf16 v[6:9], v[146:149], v[186:189], v[6:9]
	v_mfma_f32_16x16x32_bf16 v[2:5], v[154:157], v[186:189], v[2:5]
	v_mfma_f32_16x16x32_bf16 v[54:57], v[150:153], v[166:169], v[54:57]
	v_mfma_f32_16x16x32_bf16 v[50:53], v[158:161], v[166:169], v[50:53]
	v_mfma_f32_16x16x32_bf16 v[38:41], v[150:153], v[174:177], v[38:41]
	v_mfma_f32_16x16x32_bf16 v[34:37], v[158:161], v[174:177], v[34:37]
	v_mfma_f32_16x16x32_bf16 v[22:25], v[150:153], v[182:185], v[22:25]
	v_mfma_f32_16x16x32_bf16 v[18:21], v[158:161], v[182:185], v[18:21]
	v_mfma_f32_16x16x32_bf16 v[6:9], v[150:153], v[190:193], v[6:9]
	v_mfma_f32_16x16x32_bf16 v[2:5], v[158:161], v[190:193], v[2:5]
	s_setprio 1
	s_barrier
	s_add_i32 s40, s40, 2
	s_add_u32 s6, s6, 0x100
	s_addc_u32 s7, s7, 0
	s_add_u32 s35, s35, 0x100
	s_addc_u32 s37, s37, 0
	s_cmp_gt_u32 s40, 13
	s_cbranch_scc0 .LBB0_120
	s_setprio 0
	s_and_b64 vcc, exec, s[48:49]
	s_cbranch_vccz .LBB0_123
	s_barrier

.LBB0_518:
	ds_read_b128 v[148:151], v143
	ds_read_b128 v[152:155], v143 offset:1024
	ds_read_b128 v[158:161], v143 offset:2048
	ds_read_b128 v[162:165], v143 offset:3072
	ds_read_b128 v[166:169], v144
	ds_read_b128 v[170:173], v144 offset:1024
	ds_read_b128 v[174:177], v144 offset:2048
	ds_read_b128 v[178:181], v144 offset:3072
	s_add_u32 s16, s8, s10
	s_addc_u32 s17, s9, s11
	s_add_u32 s16, s16, 0x1000100
	s_addc_u32 s17, s17, 0
	s_add_u32 s44, s30, s10
	s_addc_u32 s45, s31, s11
	s_cmpk_eq_i32 s10, 0x700
	s_cselect_b32 s29, s7, s17
	s_cselect_b32 s28, s6, s16
	s_cselect_b32 s17, s5, s45
	s_cselect_b32 s16, s4, s44
	s_mov_b32 m0, s34
	v_lshl_add_u64 v[214:215], v[138:139], 0, s[10:11]
	ds_read_b128 v[182:185], v145
	ds_read_b128 v[186:189], v145 offset:1024
	ds_read_b128 v[190:193], v145 offset:2048
	ds_read_b128 v[194:197], v145 offset:3072
	ds_read_b128 v[198:201], v145 offset:4096
	ds_read_b128 v[202:205], v145 offset:5120
	ds_read_b128 v[206:209], v145 offset:6144
	ds_read_b128 v[210:213], v145 offset:7168
	global_load_lds_dwordx4 v[214:215], off
	v_lshl_add_u64 v[214:215], v[140:141], 0, s[10:11]
	s_mov_b32 m0, s35
	s_nop 0
	global_load_lds_dwordx4 v[214:215], off
	s_waitcnt vmcnt(8)
	s_waitcnt lgkmcnt(0)
	s_barrier
	s_setprio 0
	s_waitcnt lgkmcnt(0)
	v_mfma_f32_16x16x32_bf16 v[126:129], v[148:151], v[182:185], v[126:129]
	v_mfma_f32_16x16x32_bf16 v[122:125], v[158:161], v[182:185], v[122:125]
	v_mfma_f32_16x16x32_bf16 v[110:113], v[148:151], v[190:193], v[110:113]
	v_mfma_f32_16x16x32_bf16 v[106:109], v[158:161], v[190:193], v[106:109]
	v_mfma_f32_16x16x32_bf16 v[94:97], v[148:151], v[198:201], v[94:97]
	v_mfma_f32_16x16x32_bf16 v[90:93], v[158:161], v[198:201], v[90:93]
	v_mfma_f32_16x16x32_bf16 v[78:81], v[148:151], v[206:209], v[78:81]
	v_mfma_f32_16x16x32_bf16 v[74:77], v[158:161], v[206:209], v[74:77]
	v_mfma_f32_16x16x32_bf16 v[126:129], v[152:155], v[186:189], v[126:129]
	v_mfma_f32_16x16x32_bf16 v[122:125], v[162:165], v[186:189], v[122:125]
	v_mfma_f32_16x16x32_bf16 v[110:113], v[152:155], v[194:197], v[110:113]
	v_mfma_f32_16x16x32_bf16 v[106:109], v[162:165], v[194:197], v[106:109]
	v_mfma_f32_16x16x32_bf16 v[94:97], v[152:155], v[202:205], v[94:97]
	v_mfma_f32_16x16x32_bf16 v[90:93], v[162:165], v[202:205], v[90:93]
	v_mfma_f32_16x16x32_bf16 v[78:81], v[152:155], v[210:213], v[78:81]
	v_mfma_f32_16x16x32_bf16 v[74:77], v[162:165], v[210:213], v[74:77]
	s_setprio 1
	s_setprio 0
	v_mfma_f32_16x16x32_bf16 v[118:121], v[166:169], v[182:185], v[118:121]
	v_mfma_f32_16x16x32_bf16 v[114:117], v[174:177], v[182:185], v[114:117]
	v_mfma_f32_16x16x32_bf16 v[102:105], v[166:169], v[190:193], v[102:105]
	v_mfma_f32_16x16x32_bf16 v[98:101], v[174:177], v[190:193], v[98:101]
	v_mfma_f32_16x16x32_bf16 v[86:89], v[166:169], v[198:201], v[86:89]
	v_mfma_f32_16x16x32_bf16 v[82:85], v[174:177], v[198:201], v[82:85]
	v_mfma_f32_16x16x32_bf16 v[70:73], v[166:169], v[206:209], v[70:73]
	v_mfma_f32_16x16x32_bf16 v[66:69], v[174:177], v[206:209], v[66:69]
	v_mfma_f32_16x16x32_bf16 v[118:121], v[170:173], v[186:189], v[118:121]
	v_mfma_f32_16x16x32_bf16 v[114:117], v[178:181], v[186:189], v[114:117]
	v_mfma_f32_16x16x32_bf16 v[102:105], v[170:173], v[194:197], v[102:105]
	v_mfma_f32_16x16x32_bf16 v[98:101], v[178:181], v[194:197], v[98:101]
	v_mfma_f32_16x16x32_bf16 v[86:89], v[170:173], v[202:205], v[86:89]
	v_mfma_f32_16x16x32_bf16 v[82:85], v[178:181], v[202:205], v[82:85]
	v_mfma_f32_16x16x32_bf16 v[70:73], v[170:173], v[210:213], v[70:73]
	v_mfma_f32_16x16x32_bf16 v[66:69], v[178:181], v[210:213], v[66:69]
	s_setprio 1
	s_barrier
	s_mov_b32 m0, s36
	v_lshl_add_u64 v[214:215], s[16:17], 0, v[132:133]
	s_add_u32 s44, s16, 0x40000
	ds_read_b128 v[182:185], v145 offset:16384
	ds_read_b128 v[186:189], v145 offset:17408
	ds_read_b128 v[190:193], v145 offset:18432
	ds_read_b128 v[194:197], v145 offset:19456
	ds_read_b128 v[198:201], v145 offset:20480
	ds_read_b128 v[202:205], v145 offset:21504
	ds_read_b128 v[206:209], v145 offset:22528
	ds_read_b128 v[210:213], v145 offset:23552
	global_load_lds_dwordx4 v132, s[16:17]
	v_lshl_add_u64 v[216:217], s[16:17], 0, v[136:137]
	s_mov_b32 m0, s37
	s_addc_u32 s45, s17, 0
	global_load_lds_dwordx4 v136, s[16:17]
	s_mov_b32 m0, s38
	v_lshl_add_u64 v[220:221], s[28:29], 0, v[134:135]
	global_load_lds_dwordx4 v132, s[44:45]
	s_mov_b32 m0, s39
	s_nop 0
	global_load_lds_dwordx4 v136, s[44:45]
	v_lshl_add_u64 v[218:219], s[28:29], 0, v[130:131]
	s_mov_b32 m0, s1
	s_nop 0
	global_load_lds_dwordx4 v130, s[28:29]
	s_mov_b32 m0, s15
	s_nop 0
	global_load_lds_dwordx4 v134, s[28:29]
	s_waitcnt vmcnt(8)
	s_waitcnt lgkmcnt(0)
	s_barrier
	s_setprio 0
	s_waitcnt lgkmcnt(0)
	v_mfma_f32_16x16x32_bf16 v[62:65], v[148:151], v[182:185], v[62:65]
	v_mfma_f32_16x16x32_bf16 v[58:61], v[158:161], v[182:185], v[58:61]
	v_mfma_f32_16x16x32_bf16 v[46:49], v[148:151], v[190:193], v[46:49]
	v_mfma_f32_16x16x32_bf16 v[42:45], v[158:161], v[190:193], v[42:45]
	v_mfma_f32_16x16x32_bf16 v[30:33], v[148:151], v[198:201], v[30:33]
	v_mfma_f32_16x16x32_bf16 v[26:29], v[158:161], v[198:201], v[26:29]
	v_mfma_f32_16x16x32_bf16 v[14:17], v[148:151], v[206:209], v[14:17]
	v_mfma_f32_16x16x32_bf16 v[10:13], v[158:161], v[206:209], v[10:13]
	v_mfma_f32_16x16x32_bf16 v[62:65], v[152:155], v[186:189], v[62:65]
	v_mfma_f32_16x16x32_bf16 v[58:61], v[162:165], v[186:189], v[58:61]
	v_mfma_f32_16x16x32_bf16 v[46:49], v[152:155], v[194:197], v[46:49]
	v_mfma_f32_16x16x32_bf16 v[42:45], v[162:165], v[194:197], v[42:45]
	v_mfma_f32_16x16x32_bf16 v[30:33], v[152:155], v[202:205], v[30:33]
	v_mfma_f32_16x16x32_bf16 v[26:29], v[162:165], v[202:205], v[26:29]
	v_mfma_f32_16x16x32_bf16 v[14:17], v[152:155], v[210:213], v[14:17]
	v_mfma_f32_16x16x32_bf16 v[10:13], v[162:165], v[210:213], v[10:13]
	s_setprio 1
	s_setprio 0
	v_mfma_f32_16x16x32_bf16 v[54:57], v[166:169], v[182:185], v[54:57]
	v_mfma_f32_16x16x32_bf16 v[50:53], v[174:177], v[182:185], v[50:53]
	v_mfma_f32_16x16x32_bf16 v[38:41], v[166:169], v[190:193], v[38:41]
	v_mfma_f32_16x16x32_bf16 v[34:37], v[174:177], v[190:193], v[34:37]
	v_mfma_f32_16x16x32_bf16 v[22:25], v[166:169], v[198:201], v[22:25]
	v_mfma_f32_16x16x32_bf16 v[18:21], v[174:177], v[198:201], v[18:21]
	v_mfma_f32_16x16x32_bf16 v[6:9], v[166:169], v[206:209], v[6:9]
	v_mfma_f32_16x16x32_bf16 v[2:5], v[174:177], v[206:209], v[2:5]
	v_mfma_f32_16x16x32_bf16 v[54:57], v[170:173], v[186:189], v[54:57]
	v_mfma_f32_16x16x32_bf16 v[50:53], v[178:181], v[186:189], v[50:53]
	v_mfma_f32_16x16x32_bf16 v[38:41], v[170:173], v[194:197], v[38:41]
	v_mfma_f32_16x16x32_bf16 v[34:37], v[178:181], v[194:197], v[34:37]
	v_mfma_f32_16x16x32_bf16 v[22:25], v[170:173], v[202:205], v[22:25]
	v_mfma_f32_16x16x32_bf16 v[18:21], v[178:181], v[202:205], v[18:21]
	v_mfma_f32_16x16x32_bf16 v[6:9], v[170:173], v[210:213], v[6:9]
	v_mfma_f32_16x16x32_bf16 v[2:5], v[178:181], v[210:213], v[2:5]
	s_setprio 1
	s_barrier
	ds_read_b128 v[148:151], v146
	ds_read_b128 v[152:155], v146 offset:1024
	ds_read_b128 v[158:161], v146 offset:2048
	ds_read_b128 v[162:165], v146 offset:3072
	ds_read_b128 v[166:169], v147
	ds_read_b128 v[170:173], v147 offset:1024
	ds_read_b128 v[174:177], v147 offset:2048
	ds_read_b128 v[178:181], v147 offset:3072
	s_add_u32 s28, s28, 0x40000
	s_addc_u32 s29, s29, 0
	s_mov_b32 m0, s20
	ds_read_b128 v[182:185], v145 offset:32768
	ds_read_b128 v[186:189], v145 offset:33792
	ds_read_b128 v[190:193], v145 offset:34816
	ds_read_b128 v[194:197], v145 offset:35840
	ds_read_b128 v[198:201], v145 offset:36864
	ds_read_b128 v[202:205], v145 offset:37888
	ds_read_b128 v[206:209], v145 offset:38912
	ds_read_b128 v[210:213], v145 offset:39936
	global_load_lds_dwordx4 v130, s[28:29]
	s_mov_b32 m0, s21
	s_nop 0
	global_load_lds_dwordx4 v134, s[28:29]
	s_waitcnt vmcnt(8)
	s_waitcnt lgkmcnt(0)
	s_barrier
	s_setprio 0
	s_waitcnt lgkmcnt(0)
	v_mfma_f32_16x16x32_bf16 v[126:129], v[148:151], v[182:185], v[126:129]
	v_mfma_f32_16x16x32_bf16 v[122:125], v[158:161], v[182:185], v[122:125]
	v_mfma_f32_16x16x32_bf16 v[110:113], v[148:151], v[190:193], v[110:113]
	v_mfma_f32_16x16x32_bf16 v[106:109], v[158:161], v[190:193], v[106:109]
	v_mfma_f32_16x16x32_bf16 v[94:97], v[148:151], v[198:201], v[94:97]
	v_mfma_f32_16x16x32_bf16 v[90:93], v[158:161], v[198:201], v[90:93]
	v_mfma_f32_16x16x32_bf16 v[78:81], v[148:151], v[206:209], v[78:81]
	v_mfma_f32_16x16x32_bf16 v[74:77], v[158:161], v[206:209], v[74:77]
	v_mfma_f32_16x16x32_bf16 v[126:129], v[152:155], v[186:189], v[126:129]
	v_mfma_f32_16x16x32_bf16 v[122:125], v[162:165], v[186:189], v[122:125]
	v_mfma_f32_16x16x32_bf16 v[110:113], v[152:155], v[194:197], v[110:113]
	v_mfma_f32_16x16x32_bf16 v[106:109], v[162:165], v[194:197], v[106:109]
	v_mfma_f32_16x16x32_bf16 v[94:97], v[152:155], v[202:205], v[94:97]
	v_mfma_f32_16x16x32_bf16 v[90:93], v[162:165], v[202:205], v[90:93]
	v_mfma_f32_16x16x32_bf16 v[78:81], v[152:155], v[210:213], v[78:81]
	v_mfma_f32_16x16x32_bf16 v[74:77], v[162:165], v[210:213], v[74:77]
	s_setprio 1
	s_setprio 0
	v_mfma_f32_16x16x32_bf16 v[118:121], v[166:169], v[182:185], v[118:121]
	v_mfma_f32_16x16x32_bf16 v[114:117], v[174:177], v[182:185], v[114:117]
	v_mfma_f32_16x16x32_bf16 v[102:105], v[166:169], v[190:193], v[102:105]
	v_mfma_f32_16x16x32_bf16 v[98:101], v[174:177], v[190:193], v[98:101]
	v_mfma_f32_16x16x32_bf16 v[86:89], v[166:169], v[198:201], v[86:89]
	v_mfma_f32_16x16x32_bf16 v[82:85], v[174:177], v[198:201], v[82:85]
	v_mfma_f32_16x16x32_bf16 v[70:73], v[166:169], v[206:209], v[70:73]
	v_mfma_f32_16x16x32_bf16 v[66:69], v[174:177], v[206:209], v[66:69]
	v_mfma_f32_16x16x32_bf16 v[118:121], v[170:173], v[186:189], v[118:121]
	v_mfma_f32_16x16x32_bf16 v[114:117], v[178:181], v[186:189], v[114:117]
	v_mfma_f32_16x16x32_bf16 v[102:105], v[170:173], v[194:197], v[102:105]
	v_mfma_f32_16x16x32_bf16 v[98:101], v[178:181], v[194:197], v[98:101]
	v_mfma_f32_16x16x32_bf16 v[86:89], v[170:173], v[202:205], v[86:89]
	v_mfma_f32_16x16x32_bf16 v[82:85], v[178:181], v[202:205], v[82:85]
	v_mfma_f32_16x16x32_bf16 v[70:73], v[170:173], v[210:213], v[70:73]
	v_mfma_f32_16x16x32_bf16 v[66:69], v[178:181], v[210:213], v[66:69]
	s_setprio 1
	s_barrier
	s_mov_b32 m0, s40
	v_lshl_add_u64 v[214:215], v[214:215], 0, s[2:3]
	s_add_u32 s16, s16, 0x40080
	ds_read_b128 v[182:185], v145 offset:49152
	ds_read_b128 v[186:189], v145 offset:50176
	ds_read_b128 v[190:193], v145 offset:51200
	ds_read_b128 v[194:197], v145 offset:52224
	ds_read_b128 v[198:201], v145 offset:53248
	ds_read_b128 v[202:205], v145 offset:54272
	ds_read_b128 v[206:209], v145 offset:55296
	ds_read_b128 v[210:213], v145 offset:56320
	global_load_lds_dwordx4 v[214:215], off
	v_lshl_add_u64 v[214:215], v[216:217], 0, s[2:3]
	s_mov_b32 m0, s41
	s_addc_u32 s17, s17, 0
	global_load_lds_dwordx4 v[214:215], off
	s_mov_b32 m0, s42
	s_nop 0
	global_load_lds_dwordx4 v132, s[16:17]
	s_mov_b32 m0, s43
	s_nop 0
	global_load_lds_dwordx4 v136, s[16:17]
	v_lshl_add_u64 v[214:215], v[218:219], 0, s[2:3]
	s_mov_b32 m0, s22
	s_nop 0
	global_load_lds_dwordx4 v[214:215], off
	v_lshl_add_u64 v[214:215], v[220:221], 0, s[2:3]
	s_mov_b32 m0, s23
	s_nop 0
	global_load_lds_dwordx4 v[214:215], off
	s_waitcnt vmcnt(8)
	s_waitcnt lgkmcnt(0)
	s_barrier
	s_setprio 0
	s_waitcnt lgkmcnt(0)
	v_mfma_f32_16x16x32_bf16 v[62:65], v[148:151], v[182:185], v[62:65]
	v_mfma_f32_16x16x32_bf16 v[58:61], v[158:161], v[182:185], v[58:61]
	v_mfma_f32_16x16x32_bf16 v[46:49], v[148:151], v[190:193], v[46:49]
	v_mfma_f32_16x16x32_bf16 v[42:45], v[158:161], v[190:193], v[42:45]
	v_mfma_f32_16x16x32_bf16 v[30:33], v[148:151], v[198:201], v[30:33]
	v_mfma_f32_16x16x32_bf16 v[26:29], v[158:161], v[198:201], v[26:29]
	v_mfma_f32_16x16x32_bf16 v[14:17], v[148:151], v[206:209], v[14:17]
	v_mfma_f32_16x16x32_bf16 v[10:13], v[158:161], v[206:209], v[10:13]
	v_mfma_f32_16x16x32_bf16 v[62:65], v[152:155], v[186:189], v[62:65]
	v_mfma_f32_16x16x32_bf16 v[58:61], v[162:165], v[186:189], v[58:61]
	v_mfma_f32_16x16x32_bf16 v[46:49], v[152:155], v[194:197], v[46:49]
	v_mfma_f32_16x16x32_bf16 v[42:45], v[162:165], v[194:197], v[42:45]
	v_mfma_f32_16x16x32_bf16 v[30:33], v[152:155], v[202:205], v[30:33]
	v_mfma_f32_16x16x32_bf16 v[26:29], v[162:165], v[202:205], v[26:29]
	v_mfma_f32_16x16x32_bf16 v[14:17], v[152:155], v[210:213], v[14:17]
	v_mfma_f32_16x16x32_bf16 v[10:13], v[162:165], v[210:213], v[10:13]
	s_setprio 1
	s_setprio 0
	v_mfma_f32_16x16x32_bf16 v[54:57], v[166:169], v[182:185], v[54:57]
	v_mfma_f32_16x16x32_bf16 v[50:53], v[174:177], v[182:185], v[50:53]
	v_mfma_f32_16x16x32_bf16 v[38:41], v[166:169], v[190:193], v[38:41]
	v_mfma_f32_16x16x32_bf16 v[34:37], v[174:177], v[190:193], v[34:37]
	v_mfma_f32_16x16x32_bf16 v[22:25], v[166:169], v[198:201], v[22:25]
	v_mfma_f32_16x16x32_bf16 v[18:21], v[174:177], v[198:201], v[18:21]
	v_mfma_f32_16x16x32_bf16 v[6:9], v[166:169], v[206:209], v[6:9]
	v_mfma_f32_16x16x32_bf16 v[2:5], v[174:177], v[206:209], v[2:5]
	v_mfma_f32_16x16x32_bf16 v[54:57], v[170:173], v[186:189], v[54:57]
	v_mfma_f32_16x16x32_bf16 v[50:53], v[178:181], v[186:189], v[50:53]
	v_mfma_f32_16x16x32_bf16 v[38:41], v[170:173], v[194:197], v[38:41]
	v_mfma_f32_16x16x32_bf16 v[34:37], v[178:181], v[194:197], v[34:37]
	v_mfma_f32_16x16x32_bf16 v[22:25], v[170:173], v[202:205], v[22:25]
	v_mfma_f32_16x16x32_bf16 v[18:21], v[178:181], v[202:205], v[18:21]
	v_mfma_f32_16x16x32_bf16 v[6:9], v[170:173], v[210:213], v[6:9]
	v_mfma_f32_16x16x32_bf16 v[2:5], v[178:181], v[210:213], v[2:5]
	s_setprio 1
	s_barrier
	s_add_i32 s33, s33, 2
	s_add_u32 s10, s10, 0x100
	s_addc_u32 s11, s11, 0
	s_cmp_gt_u32 s33, 13
	s_cbranch_scc0 .LBB0_518
	s_setprio 0
	s_cmpk_lt_u32 s14, 0x100
	s_cbranch_scc0 .LBB0_521
	s_barrier

.LBB0_1250:
	ds_read_b128 v[146:149], v140
	ds_read_b128 v[150:153], v140 offset:1024
	ds_read_b128 v[154:157], v140 offset:2048
	ds_read_b128 v[158:161], v140 offset:3072
	ds_read_b128 v[162:165], v141
	ds_read_b128 v[166:169], v141 offset:1024
	ds_read_b128 v[170:173], v141 offset:2048
	ds_read_b128 v[174:177], v141 offset:3072
	s_add_u32 s14, s10, s12
	s_addc_u32 s15, s11, s13
	s_add_u32 s14, s14, 0x11400100
	s_addc_u32 s15, s15, 0
	s_add_u32 s39, s1, s12
	s_addc_u32 s40, s26, s13
	s_cmpk_eq_i32 s12, 0x700
	s_cselect_b32 s17, s9, s15
	s_cselect_b32 s16, s8, s14
	s_cselect_b32 s15, s7, s40
	s_cselect_b32 s14, s6, s39
	s_mov_b32 m0, s28
	v_lshl_add_u64 v[210:211], v[134:135], 0, s[12:13]
	ds_read_b128 v[178:181], v142
	ds_read_b128 v[182:185], v142 offset:1024
	ds_read_b128 v[186:189], v142 offset:2048
	ds_read_b128 v[190:193], v142 offset:3072
	ds_read_b128 v[194:197], v142 offset:4096
	ds_read_b128 v[198:201], v142 offset:5120
	ds_read_b128 v[202:205], v142 offset:6144
	ds_read_b128 v[206:209], v142 offset:7168
	global_load_lds_dwordx4 v[210:211], off
	v_lshl_add_u64 v[210:211], v[136:137], 0, s[12:13]
	s_mov_b32 m0, s29
	s_nop 0
	global_load_lds_dwordx4 v[210:211], off
	s_waitcnt vmcnt(8)
	s_waitcnt lgkmcnt(0)
	s_barrier
	s_setprio 0
	s_waitcnt lgkmcnt(0)
	v_mfma_f32_16x16x32_bf16 v[126:129], v[146:149], v[178:181], v[126:129]
	v_mfma_f32_16x16x32_bf16 v[122:125], v[154:157], v[178:181], v[122:125]
	v_mfma_f32_16x16x32_bf16 v[118:121], v[146:149], v[186:189], v[118:121]
	v_mfma_f32_16x16x32_bf16 v[114:117], v[154:157], v[186:189], v[114:117]
	v_mfma_f32_16x16x32_bf16 v[106:109], v[146:149], v[194:197], v[106:109]
	v_mfma_f32_16x16x32_bf16 v[98:101], v[154:157], v[194:197], v[98:101]
	v_mfma_f32_16x16x32_bf16 v[82:85], v[146:149], v[202:205], v[82:85]
	v_mfma_f32_16x16x32_bf16 v[74:77], v[154:157], v[202:205], v[74:77]
	v_mfma_f32_16x16x32_bf16 v[126:129], v[150:153], v[182:185], v[126:129]
	v_mfma_f32_16x16x32_bf16 v[122:125], v[158:161], v[182:185], v[122:125]
	v_mfma_f32_16x16x32_bf16 v[118:121], v[150:153], v[190:193], v[118:121]
	v_mfma_f32_16x16x32_bf16 v[114:117], v[158:161], v[190:193], v[114:117]
	v_mfma_f32_16x16x32_bf16 v[106:109], v[150:153], v[198:201], v[106:109]
	v_mfma_f32_16x16x32_bf16 v[98:101], v[158:161], v[198:201], v[98:101]
	v_mfma_f32_16x16x32_bf16 v[82:85], v[150:153], v[206:209], v[82:85]
	v_mfma_f32_16x16x32_bf16 v[74:77], v[158:161], v[206:209], v[74:77]
	s_setprio 1
	s_setprio 0
	v_mfma_f32_16x16x32_bf16 v[110:113], v[162:165], v[178:181], v[110:113]
	v_mfma_f32_16x16x32_bf16 v[102:105], v[170:173], v[178:181], v[102:105]
	v_mfma_f32_16x16x32_bf16 v[94:97], v[162:165], v[186:189], v[94:97]
	v_mfma_f32_16x16x32_bf16 v[90:93], v[170:173], v[186:189], v[90:93]
	v_mfma_f32_16x16x32_bf16 v[86:89], v[162:165], v[194:197], v[86:89]
	v_mfma_f32_16x16x32_bf16 v[78:81], v[170:173], v[194:197], v[78:81]
	v_mfma_f32_16x16x32_bf16 v[70:73], v[162:165], v[202:205], v[70:73]
	v_mfma_f32_16x16x32_bf16 v[66:69], v[170:173], v[202:205], v[66:69]
	v_mfma_f32_16x16x32_bf16 v[110:113], v[166:169], v[182:185], v[110:113]
	v_mfma_f32_16x16x32_bf16 v[102:105], v[174:177], v[182:185], v[102:105]
	v_mfma_f32_16x16x32_bf16 v[94:97], v[166:169], v[190:193], v[94:97]
	v_mfma_f32_16x16x32_bf16 v[90:93], v[174:177], v[190:193], v[90:93]
	v_mfma_f32_16x16x32_bf16 v[86:89], v[166:169], v[198:201], v[86:89]
	v_mfma_f32_16x16x32_bf16 v[78:81], v[174:177], v[198:201], v[78:81]
	v_mfma_f32_16x16x32_bf16 v[70:73], v[166:169], v[206:209], v[70:73]
	v_mfma_f32_16x16x32_bf16 v[66:69], v[174:177], v[206:209], v[66:69]
	s_setprio 1
	s_barrier
	s_mov_b32 m0, s30
	v_lshl_add_u64 v[210:211], s[14:15], 0, v[130:131]
	s_add_u32 s40, s14, 0x40000
	ds_read_b128 v[178:181], v142 offset:16384
	ds_read_b128 v[182:185], v142 offset:17408
	ds_read_b128 v[186:189], v142 offset:18432
	ds_read_b128 v[190:193], v142 offset:19456
	ds_read_b128 v[194:197], v142 offset:20480
	ds_read_b128 v[198:201], v142 offset:21504
	ds_read_b128 v[202:205], v142 offset:22528
	ds_read_b128 v[206:209], v142 offset:23552
	global_load_lds_dwordx4 v130, s[14:15]
	v_lshl_add_u64 v[212:213], s[14:15], 0, v[132:133]
	s_mov_b32 m0, s31
	s_addc_u32 s41, s15, 0
	global_load_lds_dwordx4 v132, s[14:15]
	s_mov_b32 m0, s33
	v_lshl_add_u64 v[216:217], s[16:17], 0, v[132:133]
	global_load_lds_dwordx4 v130, s[40:41]
	s_mov_b32 m0, s34
	s_nop 0
	global_load_lds_dwordx4 v132, s[40:41]
	v_lshl_add_u64 v[214:215], s[16:17], 0, v[130:131]
	s_mov_b32 m0, s5
	s_nop 0
	global_load_lds_dwordx4 v130, s[16:17]
	s_mov_b32 m0, s21
	s_nop 0
	global_load_lds_dwordx4 v132, s[16:17]
	s_waitcnt vmcnt(8)
	s_waitcnt lgkmcnt(0)
	s_barrier
	s_setprio 0
	s_waitcnt lgkmcnt(0)
	v_mfma_f32_16x16x32_bf16 v[62:65], v[146:149], v[178:181], v[62:65]
	v_mfma_f32_16x16x32_bf16 v[58:61], v[154:157], v[178:181], v[58:61]
	v_mfma_f32_16x16x32_bf16 v[54:57], v[146:149], v[186:189], v[54:57]
	v_mfma_f32_16x16x32_bf16 v[50:53], v[154:157], v[186:189], v[50:53]
	v_mfma_f32_16x16x32_bf16 v[34:37], v[146:149], v[194:197], v[34:37]
	v_mfma_f32_16x16x32_bf16 v[26:29], v[154:157], v[194:197], v[26:29]
	v_mfma_f32_16x16x32_bf16 v[22:25], v[146:149], v[202:205], v[22:25]
	v_mfma_f32_16x16x32_bf16 v[10:13], v[154:157], v[202:205], v[10:13]
	v_mfma_f32_16x16x32_bf16 v[62:65], v[150:153], v[182:185], v[62:65]
	v_mfma_f32_16x16x32_bf16 v[58:61], v[158:161], v[182:185], v[58:61]
	v_mfma_f32_16x16x32_bf16 v[54:57], v[150:153], v[190:193], v[54:57]
	v_mfma_f32_16x16x32_bf16 v[50:53], v[158:161], v[190:193], v[50:53]
	v_mfma_f32_16x16x32_bf16 v[34:37], v[150:153], v[198:201], v[34:37]
	v_mfma_f32_16x16x32_bf16 v[26:29], v[158:161], v[198:201], v[26:29]
	v_mfma_f32_16x16x32_bf16 v[22:25], v[150:153], v[206:209], v[22:25]
	v_mfma_f32_16x16x32_bf16 v[10:13], v[158:161], v[206:209], v[10:13]
	s_setprio 1
	s_setprio 0
	v_mfma_f32_16x16x32_bf16 v[46:49], v[162:165], v[178:181], v[46:49]
	v_mfma_f32_16x16x32_bf16 v[42:45], v[170:173], v[178:181], v[42:45]
	v_mfma_f32_16x16x32_bf16 v[38:41], v[162:165], v[186:189], v[38:41]
	v_mfma_f32_16x16x32_bf16 v[30:33], v[170:173], v[186:189], v[30:33]
	v_mfma_f32_16x16x32_bf16 v[18:21], v[162:165], v[194:197], v[18:21]
	v_mfma_f32_16x16x32_bf16 v[14:17], v[170:173], v[194:197], v[14:17]
	v_mfma_f32_16x16x32_bf16 v[6:9], v[162:165], v[202:205], v[6:9]
	v_mfma_f32_16x16x32_bf16 v[2:5], v[170:173], v[202:205], v[2:5]
	v_mfma_f32_16x16x32_bf16 v[46:49], v[166:169], v[182:185], v[46:49]
	v_mfma_f32_16x16x32_bf16 v[42:45], v[174:177], v[182:185], v[42:45]
	v_mfma_f32_16x16x32_bf16 v[38:41], v[166:169], v[190:193], v[38:41]
	v_mfma_f32_16x16x32_bf16 v[30:33], v[174:177], v[190:193], v[30:33]
	v_mfma_f32_16x16x32_bf16 v[18:21], v[166:169], v[198:201], v[18:21]
	v_mfma_f32_16x16x32_bf16 v[14:17], v[174:177], v[198:201], v[14:17]
	v_mfma_f32_16x16x32_bf16 v[6:9], v[166:169], v[206:209], v[6:9]
	v_mfma_f32_16x16x32_bf16 v[2:5], v[174:177], v[206:209], v[2:5]
	s_setprio 1
	s_barrier
	ds_read_b128 v[146:149], v143
	ds_read_b128 v[150:153], v143 offset:1024
	ds_read_b128 v[154:157], v143 offset:2048
	ds_read_b128 v[158:161], v143 offset:3072
	ds_read_b128 v[162:165], v144
	ds_read_b128 v[166:169], v144 offset:1024
	ds_read_b128 v[170:173], v144 offset:2048
	ds_read_b128 v[174:177], v144 offset:3072
	s_add_u32 s16, s16, 0x40000
	s_addc_u32 s17, s17, 0
	s_mov_b32 m0, s22
	ds_read_b128 v[178:181], v142 offset:32768
	ds_read_b128 v[182:185], v142 offset:33792
	ds_read_b128 v[186:189], v142 offset:34816
	ds_read_b128 v[190:193], v142 offset:35840
	ds_read_b128 v[194:197], v142 offset:36864
	ds_read_b128 v[198:201], v142 offset:37888
	ds_read_b128 v[202:205], v142 offset:38912
	ds_read_b128 v[206:209], v142 offset:39936
	global_load_lds_dwordx4 v130, s[16:17]
	s_mov_b32 m0, s23
	s_nop 0
	global_load_lds_dwordx4 v132, s[16:17]
	s_waitcnt vmcnt(8)
	s_waitcnt lgkmcnt(0)
	s_barrier
	s_setprio 0
	s_waitcnt lgkmcnt(0)
	v_mfma_f32_16x16x32_bf16 v[126:129], v[146:149], v[178:181], v[126:129]
	v_mfma_f32_16x16x32_bf16 v[122:125], v[154:157], v[178:181], v[122:125]
	v_mfma_f32_16x16x32_bf16 v[118:121], v[146:149], v[186:189], v[118:121]
	v_mfma_f32_16x16x32_bf16 v[114:117], v[154:157], v[186:189], v[114:117]
	v_mfma_f32_16x16x32_bf16 v[106:109], v[146:149], v[194:197], v[106:109]
	v_mfma_f32_16x16x32_bf16 v[98:101], v[154:157], v[194:197], v[98:101]
	v_mfma_f32_16x16x32_bf16 v[82:85], v[146:149], v[202:205], v[82:85]
	v_mfma_f32_16x16x32_bf16 v[74:77], v[154:157], v[202:205], v[74:77]
	v_mfma_f32_16x16x32_bf16 v[126:129], v[150:153], v[182:185], v[126:129]
	v_mfma_f32_16x16x32_bf16 v[122:125], v[158:161], v[182:185], v[122:125]
	v_mfma_f32_16x16x32_bf16 v[118:121], v[150:153], v[190:193], v[118:121]
	v_mfma_f32_16x16x32_bf16 v[114:117], v[158:161], v[190:193], v[114:117]
	v_mfma_f32_16x16x32_bf16 v[106:109], v[150:153], v[198:201], v[106:109]
	v_mfma_f32_16x16x32_bf16 v[98:101], v[158:161], v[198:201], v[98:101]
	v_mfma_f32_16x16x32_bf16 v[82:85], v[150:153], v[206:209], v[82:85]
	v_mfma_f32_16x16x32_bf16 v[74:77], v[158:161], v[206:209], v[74:77]
	s_setprio 1
	s_setprio 0
	v_mfma_f32_16x16x32_bf16 v[110:113], v[162:165], v[178:181], v[110:113]
	v_mfma_f32_16x16x32_bf16 v[102:105], v[170:173], v[178:181], v[102:105]
	v_mfma_f32_16x16x32_bf16 v[94:97], v[162:165], v[186:189], v[94:97]
	v_mfma_f32_16x16x32_bf16 v[90:93], v[170:173], v[186:189], v[90:93]
	v_mfma_f32_16x16x32_bf16 v[86:89], v[162:165], v[194:197], v[86:89]
	v_mfma_f32_16x16x32_bf16 v[78:81], v[170:173], v[194:197], v[78:81]
	v_mfma_f32_16x16x32_bf16 v[70:73], v[162:165], v[202:205], v[70:73]
	v_mfma_f32_16x16x32_bf16 v[66:69], v[170:173], v[202:205], v[66:69]
	v_mfma_f32_16x16x32_bf16 v[110:113], v[166:169], v[182:185], v[110:113]
	v_mfma_f32_16x16x32_bf16 v[102:105], v[174:177], v[182:185], v[102:105]
	v_mfma_f32_16x16x32_bf16 v[94:97], v[166:169], v[190:193], v[94:97]
	v_mfma_f32_16x16x32_bf16 v[90:93], v[174:177], v[190:193], v[90:93]
	v_mfma_f32_16x16x32_bf16 v[86:89], v[166:169], v[198:201], v[86:89]
	v_mfma_f32_16x16x32_bf16 v[78:81], v[174:177], v[198:201], v[78:81]
	v_mfma_f32_16x16x32_bf16 v[70:73], v[166:169], v[206:209], v[70:73]
	v_mfma_f32_16x16x32_bf16 v[66:69], v[174:177], v[206:209], v[66:69]
	s_setprio 1
	s_barrier
	s_mov_b32 m0, s35
	v_lshl_add_u64 v[210:211], v[210:211], 0, s[2:3]
	s_add_u32 s14, s14, 0x40080
	ds_read_b128 v[178:181], v142 offset:49152
	ds_read_b128 v[182:185], v142 offset:50176
	ds_read_b128 v[186:189], v142 offset:51200
	ds_read_b128 v[190:193], v142 offset:52224
	ds_read_b128 v[194:197], v142 offset:53248
	ds_read_b128 v[198:201], v142 offset:54272
	ds_read_b128 v[202:205], v142 offset:55296
	ds_read_b128 v[206:209], v142 offset:56320
	global_load_lds_dwordx4 v[210:211], off
	v_lshl_add_u64 v[210:211], v[212:213], 0, s[2:3]
	s_mov_b32 m0, s36
	s_addc_u32 s15, s15, 0
	global_load_lds_dwordx4 v[210:211], off
	s_mov_b32 m0, s37
	s_nop 0
	global_load_lds_dwordx4 v130, s[14:15]
	s_mov_b32 m0, s38
	s_nop 0
	global_load_lds_dwordx4 v132, s[14:15]
	v_lshl_add_u64 v[210:211], v[214:215], 0, s[2:3]
	s_mov_b32 m0, s24
	s_nop 0
	global_load_lds_dwordx4 v[210:211], off
	v_lshl_add_u64 v[210:211], v[216:217], 0, s[2:3]
	s_mov_b32 m0, s25
	s_nop 0
	global_load_lds_dwordx4 v[210:211], off
	s_waitcnt vmcnt(8)
	s_waitcnt lgkmcnt(0)
	s_barrier
	s_setprio 0
	s_waitcnt lgkmcnt(0)
	v_mfma_f32_16x16x32_bf16 v[62:65], v[146:149], v[178:181], v[62:65]
	v_mfma_f32_16x16x32_bf16 v[58:61], v[154:157], v[178:181], v[58:61]
	v_mfma_f32_16x16x32_bf16 v[54:57], v[146:149], v[186:189], v[54:57]
	v_mfma_f32_16x16x32_bf16 v[50:53], v[154:157], v[186:189], v[50:53]
	v_mfma_f32_16x16x32_bf16 v[34:37], v[146:149], v[194:197], v[34:37]
	v_mfma_f32_16x16x32_bf16 v[26:29], v[154:157], v[194:197], v[26:29]
	v_mfma_f32_16x16x32_bf16 v[22:25], v[146:149], v[202:205], v[22:25]
	v_mfma_f32_16x16x32_bf16 v[10:13], v[154:157], v[202:205], v[10:13]
	v_mfma_f32_16x16x32_bf16 v[62:65], v[150:153], v[182:185], v[62:65]
	v_mfma_f32_16x16x32_bf16 v[58:61], v[158:161], v[182:185], v[58:61]
	v_mfma_f32_16x16x32_bf16 v[54:57], v[150:153], v[190:193], v[54:57]
	v_mfma_f32_16x16x32_bf16 v[50:53], v[158:161], v[190:193], v[50:53]
	v_mfma_f32_16x16x32_bf16 v[34:37], v[150:153], v[198:201], v[34:37]
	v_mfma_f32_16x16x32_bf16 v[26:29], v[158:161], v[198:201], v[26:29]
	v_mfma_f32_16x16x32_bf16 v[22:25], v[150:153], v[206:209], v[22:25]
	v_mfma_f32_16x16x32_bf16 v[10:13], v[158:161], v[206:209], v[10:13]
	s_setprio 1
	s_setprio 0
	v_mfma_f32_16x16x32_bf16 v[46:49], v[162:165], v[178:181], v[46:49]
	v_mfma_f32_16x16x32_bf16 v[42:45], v[170:173], v[178:181], v[42:45]
	v_mfma_f32_16x16x32_bf16 v[38:41], v[162:165], v[186:189], v[38:41]
	v_mfma_f32_16x16x32_bf16 v[30:33], v[170:173], v[186:189], v[30:33]
	v_mfma_f32_16x16x32_bf16 v[18:21], v[162:165], v[194:197], v[18:21]
	v_mfma_f32_16x16x32_bf16 v[14:17], v[170:173], v[194:197], v[14:17]
	v_mfma_f32_16x16x32_bf16 v[6:9], v[162:165], v[202:205], v[6:9]
	v_mfma_f32_16x16x32_bf16 v[2:5], v[170:173], v[202:205], v[2:5]
	v_mfma_f32_16x16x32_bf16 v[46:49], v[166:169], v[182:185], v[46:49]
	v_mfma_f32_16x16x32_bf16 v[42:45], v[174:177], v[182:185], v[42:45]
	v_mfma_f32_16x16x32_bf16 v[38:41], v[166:169], v[190:193], v[38:41]
	v_mfma_f32_16x16x32_bf16 v[30:33], v[174:177], v[190:193], v[30:33]
	v_mfma_f32_16x16x32_bf16 v[18:21], v[166:169], v[198:201], v[18:21]
	v_mfma_f32_16x16x32_bf16 v[14:17], v[174:177], v[198:201], v[14:17]
	v_mfma_f32_16x16x32_bf16 v[6:9], v[166:169], v[206:209], v[6:9]
	v_mfma_f32_16x16x32_bf16 v[2:5], v[174:177], v[206:209], v[2:5]
	s_setprio 1
	s_barrier
	s_add_i32 s27, s27, 2
	s_add_u32 s12, s12, 0x100
	s_addc_u32 s13, s13, 0
	s_cmp_gt_u32 s27, 13
	s_cbranch_scc0 .LBB0_1250
	s_setprio 0
	s_cmpk_lt_u32 s19, 0x100
	s_cbranch_scc0 .LBB0_1253
	s_barrier

.LBB0_1381:
	ds_read_b128 v[138:141], v147
	ds_read_b128 v[150:153], v147 offset:1024
	ds_read_b128 v[154:157], v147 offset:2048
	ds_read_b128 v[158:161], v147 offset:3072
	ds_read_b128 v[162:165], v148
	ds_read_b128 v[166:169], v148 offset:1024
	ds_read_b128 v[170:173], v148 offset:2048
	ds_read_b128 v[174:177], v148 offset:3072
	s_add_u32 s24, s2, 0xfffc0080
	s_addc_u32 s25, s3, -1
	s_cmp_eq_u32 s53, 12
	s_cselect_b32 s27, s17, s25
	s_cselect_b32 s26, s49, s24
	s_cselect_b32 s25, s15, s52
	s_cselect_b32 s24, s50, s51
	s_add_i32 m0, s23, 0xc000
	ds_read_b128 v[178:181], v149
	ds_read_b128 v[182:185], v149 offset:1024
	ds_read_b128 v[186:189], v149 offset:2048
	ds_read_b128 v[190:193], v149 offset:3072
	ds_read_b128 v[194:197], v149 offset:4096
	ds_read_b128 v[198:201], v149 offset:5120
	ds_read_b128 v[202:205], v149 offset:6144
	ds_read_b128 v[206:209], v149 offset:7168
	global_load_lds_dwordx4 v132, s[2:3]
	s_add_i32 m0, s23, 0xe000
	s_nop 0
	global_load_lds_dwordx4 v134, s[2:3]
	s_waitcnt vmcnt(8)
	s_waitcnt lgkmcnt(0)
	s_barrier
	s_setprio 0
	s_waitcnt lgkmcnt(0)
	v_mfma_f32_16x16x32_bf16 v[124:127], v[138:141], v[178:181], v[124:127]
	v_mfma_f32_16x16x32_bf16 v[120:123], v[154:157], v[178:181], v[120:123]
	v_mfma_f32_16x16x32_bf16 v[116:119], v[138:141], v[186:189], v[116:119]
	v_mfma_f32_16x16x32_bf16 v[112:115], v[154:157], v[186:189], v[112:115]
	v_mfma_f32_16x16x32_bf16 v[104:107], v[138:141], v[194:197], v[104:107]
	v_mfma_f32_16x16x32_bf16 v[96:99], v[154:157], v[194:197], v[96:99]
	v_mfma_f32_16x16x32_bf16 v[88:91], v[138:141], v[202:205], v[88:91]
	v_mfma_f32_16x16x32_bf16 v[80:83], v[154:157], v[202:205], v[80:83]
	v_mfma_f32_16x16x32_bf16 v[124:127], v[150:153], v[182:185], v[124:127]
	v_mfma_f32_16x16x32_bf16 v[120:123], v[158:161], v[182:185], v[120:123]
	v_mfma_f32_16x16x32_bf16 v[116:119], v[150:153], v[190:193], v[116:119]
	v_mfma_f32_16x16x32_bf16 v[112:115], v[158:161], v[190:193], v[112:115]
	v_mfma_f32_16x16x32_bf16 v[104:107], v[150:153], v[198:201], v[104:107]
	v_mfma_f32_16x16x32_bf16 v[96:99], v[158:161], v[198:201], v[96:99]
	v_mfma_f32_16x16x32_bf16 v[88:91], v[150:153], v[206:209], v[88:91]
	v_mfma_f32_16x16x32_bf16 v[80:83], v[158:161], v[206:209], v[80:83]
	s_setprio 1
	s_setprio 0
	v_mfma_f32_16x16x32_bf16 v[108:111], v[162:165], v[178:181], v[108:111]
	v_mfma_f32_16x16x32_bf16 v[100:103], v[170:173], v[178:181], v[100:103]
	v_mfma_f32_16x16x32_bf16 v[92:95], v[162:165], v[186:189], v[92:95]
	v_mfma_f32_16x16x32_bf16 v[84:87], v[170:173], v[186:189], v[84:87]
	v_mfma_f32_16x16x32_bf16 v[76:79], v[162:165], v[194:197], v[76:79]
	v_mfma_f32_16x16x32_bf16 v[72:75], v[170:173], v[194:197], v[72:75]
	v_mfma_f32_16x16x32_bf16 v[68:71], v[162:165], v[202:205], v[68:71]
	v_mfma_f32_16x16x32_bf16 v[64:67], v[170:173], v[202:205], v[64:67]
	v_mfma_f32_16x16x32_bf16 v[108:111], v[166:169], v[182:185], v[108:111]
	v_mfma_f32_16x16x32_bf16 v[100:103], v[174:177], v[182:185], v[100:103]
	v_mfma_f32_16x16x32_bf16 v[92:95], v[166:169], v[190:193], v[92:95]
	v_mfma_f32_16x16x32_bf16 v[84:87], v[174:177], v[190:193], v[84:87]
	v_mfma_f32_16x16x32_bf16 v[76:79], v[166:169], v[198:201], v[76:79]
	v_mfma_f32_16x16x32_bf16 v[72:75], v[174:177], v[198:201], v[72:75]
	v_mfma_f32_16x16x32_bf16 v[68:71], v[166:169], v[206:209], v[68:71]
	v_mfma_f32_16x16x32_bf16 v[64:67], v[174:177], v[206:209], v[64:67]
	s_setprio 1
	s_barrier
	s_add_i32 s54, s4, s29
	s_mov_b32 m0, s54
	ds_read_b128 v[178:181], v149 offset:16384
	ds_read_b128 v[182:185], v149 offset:17408
	ds_read_b128 v[186:189], v149 offset:18432
	ds_read_b128 v[190:193], v149 offset:19456
	ds_read_b128 v[194:197], v149 offset:20480
	ds_read_b128 v[198:201], v149 offset:21504
	ds_read_b128 v[202:205], v149 offset:22528
	ds_read_b128 v[206:209], v149 offset:23552
	global_load_lds_dwordx4 v130, s[24:25]
	s_add_i32 m0, s54, 0x2000
	s_add_u32 s54, s24, 0x40000
	s_addc_u32 s55, s25, 0
	s_add_i32 s56, s41, s29
	global_load_lds_dwordx4 v128, s[24:25]
	s_mov_b32 m0, s56
	v_lshl_add_u64 v[214:215], s[26:27], 0, v[128:129]
	global_load_lds_dwordx4 v130, s[54:55]
	s_add_i32 m0, s56, 0x2000
	s_nop 0
	global_load_lds_dwordx4 v128, s[54:55]
	v_lshl_add_u64 v[212:213], s[26:27], 0, v[130:131]
	s_mov_b32 m0, s23
	s_nop 0
	global_load_lds_dwordx4 v130, s[26:27]
	s_mov_b32 m0, s34
	s_nop 0
	global_load_lds_dwordx4 v128, s[26:27]
	s_waitcnt vmcnt(8)
	s_waitcnt lgkmcnt(0)
	s_barrier
	s_setprio 0
	s_waitcnt lgkmcnt(0)
	v_mfma_f32_16x16x32_bf16 v[60:63], v[138:141], v[178:181], v[60:63]
	v_mfma_f32_16x16x32_bf16 v[56:59], v[154:157], v[178:181], v[56:59]
	v_mfma_f32_16x16x32_bf16 v[52:55], v[138:141], v[186:189], v[52:55]
	v_mfma_f32_16x16x32_bf16 v[48:51], v[154:157], v[186:189], v[48:51]
	v_mfma_f32_16x16x32_bf16 v[44:47], v[138:141], v[194:197], v[44:47]
	v_mfma_f32_16x16x32_bf16 v[32:35], v[154:157], v[194:197], v[32:35]
	v_mfma_f32_16x16x32_bf16 v[20:23], v[138:141], v[202:205], v[20:23]
	v_mfma_f32_16x16x32_bf16 v[8:11], v[154:157], v[202:205], v[8:11]
	v_mfma_f32_16x16x32_bf16 v[60:63], v[150:153], v[182:185], v[60:63]
	v_mfma_f32_16x16x32_bf16 v[56:59], v[158:161], v[182:185], v[56:59]
	v_mfma_f32_16x16x32_bf16 v[52:55], v[150:153], v[190:193], v[52:55]
	v_mfma_f32_16x16x32_bf16 v[48:51], v[158:161], v[190:193], v[48:51]
	v_mfma_f32_16x16x32_bf16 v[44:47], v[150:153], v[198:201], v[44:47]
	v_mfma_f32_16x16x32_bf16 v[32:35], v[158:161], v[198:201], v[32:35]
	v_mfma_f32_16x16x32_bf16 v[20:23], v[150:153], v[206:209], v[20:23]
	v_mfma_f32_16x16x32_bf16 v[8:11], v[158:161], v[206:209], v[8:11]
	s_setprio 1
	s_setprio 0
	v_mfma_f32_16x16x32_bf16 v[40:43], v[162:165], v[178:181], v[40:43]
	v_mfma_f32_16x16x32_bf16 v[36:39], v[170:173], v[178:181], v[36:39]
	v_mfma_f32_16x16x32_bf16 v[28:31], v[162:165], v[186:189], v[28:31]
	v_mfma_f32_16x16x32_bf16 v[24:27], v[170:173], v[186:189], v[24:27]
	v_mfma_f32_16x16x32_bf16 v[16:19], v[162:165], v[194:197], v[16:19]
	v_mfma_f32_16x16x32_bf16 v[12:15], v[170:173], v[194:197], v[12:15]
	v_mfma_f32_16x16x32_bf16 v[4:7], v[162:165], v[202:205], v[4:7]
	v_mfma_f32_16x16x32_bf16 v[0:3], v[170:173], v[202:205], v[0:3]
	v_mfma_f32_16x16x32_bf16 v[40:43], v[166:169], v[182:185], v[40:43]
	v_mfma_f32_16x16x32_bf16 v[36:39], v[174:177], v[182:185], v[36:39]
	v_mfma_f32_16x16x32_bf16 v[28:31], v[166:169], v[190:193], v[28:31]
	v_mfma_f32_16x16x32_bf16 v[24:27], v[174:177], v[190:193], v[24:27]
	v_mfma_f32_16x16x32_bf16 v[16:19], v[166:169], v[198:201], v[16:19]
	v_mfma_f32_16x16x32_bf16 v[12:15], v[174:177], v[198:201], v[12:15]
	v_mfma_f32_16x16x32_bf16 v[4:7], v[166:169], v[206:209], v[4:7]
	v_mfma_f32_16x16x32_bf16 v[0:3], v[174:177], v[206:209], v[0:3]
	s_setprio 1
	s_barrier
	s_add_i32 s54, 0, 0x18000
	s_add_i32 s55, 0, 0x1c000
	v_add_u32_e32 v158, s54, v145
	v_add_u32_e32 v174, s55, v145
	ds_read_b128 v[138:141], v158
	ds_read_b128 v[150:153], v158 offset:1024
	ds_read_b128 v[154:157], v158 offset:2048
	ds_read_b128 v[158:161], v158 offset:3072
	ds_read_b128 v[162:165], v174
	ds_read_b128 v[166:169], v174 offset:1024
	ds_read_b128 v[170:173], v174 offset:2048
	ds_read_b128 v[174:177], v174 offset:3072
	s_add_u32 s26, s26, 0x40000
	s_addc_u32 s27, s27, 0
	s_mov_b32 m0, s35
	ds_read_b128 v[178:181], v149 offset:32768
	ds_read_b128 v[182:185], v149 offset:33792
	ds_read_b128 v[186:189], v149 offset:34816
	ds_read_b128 v[190:193], v149 offset:35840
	ds_read_b128 v[194:197], v149 offset:36864
	ds_read_b128 v[198:201], v149 offset:37888
	ds_read_b128 v[202:205], v149 offset:38912
	ds_read_b128 v[206:209], v149 offset:39936
	global_load_lds_dwordx4 v130, s[26:27]
	s_mov_b32 m0, s36
	s_nop 0
	global_load_lds_dwordx4 v128, s[26:27]
	s_waitcnt vmcnt(8)
	s_waitcnt lgkmcnt(0)
	s_barrier
	s_setprio 0
	s_waitcnt lgkmcnt(0)
	v_mfma_f32_16x16x32_bf16 v[124:127], v[138:141], v[178:181], v[124:127]
	v_mfma_f32_16x16x32_bf16 v[120:123], v[154:157], v[178:181], v[120:123]
	v_mfma_f32_16x16x32_bf16 v[116:119], v[138:141], v[186:189], v[116:119]
	v_mfma_f32_16x16x32_bf16 v[112:115], v[154:157], v[186:189], v[112:115]
	v_mfma_f32_16x16x32_bf16 v[104:107], v[138:141], v[194:197], v[104:107]
	v_mfma_f32_16x16x32_bf16 v[96:99], v[154:157], v[194:197], v[96:99]
	v_mfma_f32_16x16x32_bf16 v[88:91], v[138:141], v[202:205], v[88:91]
	v_mfma_f32_16x16x32_bf16 v[80:83], v[154:157], v[202:205], v[80:83]
	v_mfma_f32_16x16x32_bf16 v[124:127], v[150:153], v[182:185], v[124:127]
	v_mfma_f32_16x16x32_bf16 v[120:123], v[158:161], v[182:185], v[120:123]
	v_mfma_f32_16x16x32_bf16 v[116:119], v[150:153], v[190:193], v[116:119]
	v_mfma_f32_16x16x32_bf16 v[112:115], v[158:161], v[190:193], v[112:115]
	v_mfma_f32_16x16x32_bf16 v[104:107], v[150:153], v[198:201], v[104:107]
	v_mfma_f32_16x16x32_bf16 v[96:99], v[158:161], v[198:201], v[96:99]
	v_mfma_f32_16x16x32_bf16 v[88:91], v[150:153], v[206:209], v[88:91]
	v_mfma_f32_16x16x32_bf16 v[80:83], v[158:161], v[206:209], v[80:83]
	s_setprio 1
	s_setprio 0
	v_mfma_f32_16x16x32_bf16 v[108:111], v[162:165], v[178:181], v[108:111]
	v_mfma_f32_16x16x32_bf16 v[100:103], v[170:173], v[178:181], v[100:103]
	v_mfma_f32_16x16x32_bf16 v[92:95], v[162:165], v[186:189], v[92:95]
	v_mfma_f32_16x16x32_bf16 v[84:87], v[170:173], v[186:189], v[84:87]
	v_mfma_f32_16x16x32_bf16 v[76:79], v[162:165], v[194:197], v[76:79]
	v_mfma_f32_16x16x32_bf16 v[72:75], v[170:173], v[194:197], v[72:75]
	v_mfma_f32_16x16x32_bf16 v[68:71], v[162:165], v[202:205], v[68:71]
	v_mfma_f32_16x16x32_bf16 v[64:67], v[170:173], v[202:205], v[64:67]
	v_mfma_f32_16x16x32_bf16 v[108:111], v[166:169], v[182:185], v[108:111]
	v_mfma_f32_16x16x32_bf16 v[100:103], v[174:177], v[182:185], v[100:103]
	v_mfma_f32_16x16x32_bf16 v[92:95], v[166:169], v[190:193], v[92:95]
	v_mfma_f32_16x16x32_bf16 v[84:87], v[174:177], v[190:193], v[84:87]
	v_mfma_f32_16x16x32_bf16 v[76:79], v[166:169], v[198:201], v[76:79]
	v_mfma_f32_16x16x32_bf16 v[72:75], v[174:177], v[198:201], v[72:75]
	v_mfma_f32_16x16x32_bf16 v[68:71], v[166:169], v[206:209], v[68:71]
	v_mfma_f32_16x16x32_bf16 v[64:67], v[174:177], v[206:209], v[64:67]
	s_setprio 1
	s_barrier
	s_add_i32 s26, s54, s29
	s_add_i32 m0, s26, 0xffffff80
	ds_read_b128 v[178:181], v149 offset:49152
	ds_read_b128 v[182:185], v149 offset:50176
	ds_read_b128 v[186:189], v149 offset:51200
	ds_read_b128 v[190:193], v149 offset:52224
	ds_read_b128 v[194:197], v149 offset:53248
	ds_read_b128 v[198:201], v149 offset:54272
	ds_read_b128 v[202:205], v149 offset:55296
	ds_read_b128 v[206:209], v149 offset:56320
	global_load_lds_dwordx4 v130, s[24:25] offset:128
	s_add_i32 m0, s26, 0x1f80
	s_add_i32 s26, s55, s29
	global_load_lds_dwordx4 v128, s[24:25] offset:128
	s_add_u32 s24, s24, 0x40080
	s_addc_u32 s25, s25, 0
	s_mov_b32 m0, s26
	s_nop 0
	global_load_lds_dwordx4 v130, s[24:25]
	s_add_i32 m0, s26, 0x2000
	s_nop 0
	global_load_lds_dwordx4 v128, s[24:25]
	v_lshl_add_u64 v[142:143], v[212:213], 0, s[8:9]
	s_mov_b32 m0, s38
	s_nop 0
	global_load_lds_dwordx4 v[142:143], off
	v_lshl_add_u64 v[142:143], v[214:215], 0, s[8:9]
	s_mov_b32 m0, s39
	s_nop 0
	global_load_lds_dwordx4 v[142:143], off
	s_waitcnt vmcnt(8)
	s_waitcnt lgkmcnt(0)
	s_barrier
	s_setprio 0
	s_waitcnt lgkmcnt(0)
	v_mfma_f32_16x16x32_bf16 v[60:63], v[138:141], v[178:181], v[60:63]
	v_mfma_f32_16x16x32_bf16 v[56:59], v[154:157], v[178:181], v[56:59]
	v_mfma_f32_16x16x32_bf16 v[52:55], v[138:141], v[186:189], v[52:55]
	v_mfma_f32_16x16x32_bf16 v[48:51], v[154:157], v[186:189], v[48:51]
	v_mfma_f32_16x16x32_bf16 v[44:47], v[138:141], v[194:197], v[44:47]
	v_mfma_f32_16x16x32_bf16 v[32:35], v[154:157], v[194:197], v[32:35]
	v_mfma_f32_16x16x32_bf16 v[20:23], v[138:141], v[202:205], v[20:23]
	v_mfma_f32_16x16x32_bf16 v[8:11], v[154:157], v[202:205], v[8:11]
	v_mfma_f32_16x16x32_bf16 v[60:63], v[150:153], v[182:185], v[60:63]
	v_mfma_f32_16x16x32_bf16 v[56:59], v[158:161], v[182:185], v[56:59]
	v_mfma_f32_16x16x32_bf16 v[52:55], v[150:153], v[190:193], v[52:55]
	v_mfma_f32_16x16x32_bf16 v[48:51], v[158:161], v[190:193], v[48:51]
	v_mfma_f32_16x16x32_bf16 v[44:47], v[150:153], v[198:201], v[44:47]
	v_mfma_f32_16x16x32_bf16 v[32:35], v[158:161], v[198:201], v[32:35]
	v_mfma_f32_16x16x32_bf16 v[20:23], v[150:153], v[206:209], v[20:23]
	v_mfma_f32_16x16x32_bf16 v[8:11], v[158:161], v[206:209], v[8:11]
	s_setprio 1
	s_setprio 0
	v_mfma_f32_16x16x32_bf16 v[40:43], v[162:165], v[178:181], v[40:43]
	v_mfma_f32_16x16x32_bf16 v[36:39], v[170:173], v[178:181], v[36:39]
	v_mfma_f32_16x16x32_bf16 v[28:31], v[162:165], v[186:189], v[28:31]
	v_mfma_f32_16x16x32_bf16 v[24:27], v[170:173], v[186:189], v[24:27]
	v_mfma_f32_16x16x32_bf16 v[16:19], v[162:165], v[194:197], v[16:19]
	v_mfma_f32_16x16x32_bf16 v[12:15], v[170:173], v[194:197], v[12:15]
	v_mfma_f32_16x16x32_bf16 v[4:7], v[162:165], v[202:205], v[4:7]
	v_mfma_f32_16x16x32_bf16 v[0:3], v[170:173], v[202:205], v[0:3]
	v_mfma_f32_16x16x32_bf16 v[40:43], v[166:169], v[182:185], v[40:43]
	v_mfma_f32_16x16x32_bf16 v[36:39], v[174:177], v[182:185], v[36:39]
	v_mfma_f32_16x16x32_bf16 v[28:31], v[166:169], v[190:193], v[28:31]
	v_mfma_f32_16x16x32_bf16 v[24:27], v[174:177], v[190:193], v[24:27]
	v_mfma_f32_16x16x32_bf16 v[16:19], v[166:169], v[198:201], v[16:19]
	v_mfma_f32_16x16x32_bf16 v[12:15], v[174:177], v[198:201], v[12:15]
	v_mfma_f32_16x16x32_bf16 v[4:7], v[166:169], v[206:209], v[4:7]
	v_mfma_f32_16x16x32_bf16 v[0:3], v[174:177], v[206:209], v[0:3]
	s_setprio 1
	s_barrier
	s_add_i32 s53, s53, 2
	s_add_u32 s2, s2, 0x100
	s_addc_u32 s3, s3, 0
	s_add_u32 s51, s51, 0x100
	s_addc_u32 s52, s52, 0
	s_cmp_gt_u32 s53, 13
	s_cbranch_scc0 .LBB0_1381
	s_setprio 0
	s_and_b64 vcc, exec, s[10:11]
	s_cbranch_vccz .LBB0_1384
	s_barrier
